# prologue conversion loop: only the join wait before the 8th load relaxed to vmcnt(7) (16 loads in flight, store drain at iteration top kept); on top of prep6
# speedup vs baseline: 1.0022x; 1.0022x over previous
; #define CV_MAP(g_, l_, it_) do { (l_) = lfix; \
;         if (MODE == 2) (it_) = CV_S0 + base + (g_); \
;         else if (MODE == 1) (it_) = cv_ritem(g_); \
;         else if ((g_) < CV_NR) (it_) = cv_ritem(g_); \
;         else { const int q_ = ((g_) - CV_NR) / CV_RPRO; (l_) = 1 + q_; (it_) = cv_ritem(CV_DEFER + ((g_) - CV_NR) - q_ * CV_RPRO); } } while (0)
; __device__ __forceinline__ void p0_item_load(const float* W, int N, int item, int lane, f32x4 (&wv)[8]) {
;     const int nblk = N / 32, kb = item / nblk, nb = item % nblk, k0 = 64 * kb, n0 = 32 * nb;
; #pragma unroll
;     for (int i = 0; i < 8; ++i) wv[i] = *(const f32x4*)(W + (size_t)(k0 + 8 * i + (lane >> 3)) * N + n0 + 4 * (lane & 7));
; }
; __device__ __forceinline__ void cv_load(const Args& a, int l, int it, int lane, f32x4 (&wv)[8]) {
;     ...
;     else if (it < CV_B) p0_item_load(a.in[I_WOUT] + (size_t)l * DM * DM, DM, it - CV_A, lane, wv);
;     else if (it < CV_C) p0_item_load(a.in[I_W1] + (size_t)l * DM * DFF, DFF, it - CV_B, lane, wv);
;     else p0_item_load(a.in[I_W2] + (size_t)l * DFF * DM, DM, it - CV_C, lane, wv);
; template <int MODE>
; __device__ __forceinline__ void cv_jobs(const Frame& F, const Args& a, int lfix, int base, int njobs, int w, int nw) {
;     ...
;     for (int g = w; g < njobs; g += 2 * nw) {
;         const int g1 = g + nw; int l, it, l1, it1; CV_MAP(g, l, it); CV_MAP(g1, l1, it1);
;         cv_load(a, l, it, F.lane, sa);
;         if (g1 < njobs) cv_load(a, l1, it1, F.lane, sb);
.LBB0_31:
	s_waitcnt vmcnt(7)
	global_load_dwordx4 v[60:63], v[60:61], off nt
	s_cmpk_lt_i32 s51, 0x3fe0
	s_cselect_b64 s[82:83], -1, 0
	s_cmpk_gt_i32 s51, 0x3fdf
	s_cbranch_scc1 .LBB0_47
	s_cmpk_gt_i32 s48, 0x161f
	s_mov_b64 s[84:85], -1
	s_cbranch_scc0 .LBB0_42
	s_cmpk_gt_u32 s48, 0x1e1f
	s_cbranch_scc0 .LBB0_39
	s_lshl_b64 s[84:85], s[78:79], 26
	s_cmpk_gt_u32 s48, 0x3e1f
	s_mov_b64 s[86:87], -1
	s_cbranch_scc0 .LBB0_36
	s_add_u32 s51, s8, s84
	s_addc_u32 s53, s9, s85
	s_add_i32 s52, s48, 0xffffc1e0
	s_and_b32 s54, s52, 0xffffffc0
	s_lshl_b32 s52, s52, 7
	v_add_u32_e32 v2, s54, v69
	s_and_b32 s52, s52, 0x1f80
	s_add_u32 s52, s51, s52
	v_add_u32_e32 v10, 24, v2
	s_addc_u32 s53, s53, 0
	v_ashrrev_i32_e32 v11, 31, v10
	v_lshl_add_u64 v[6:7], s[52:53], 0, v[64:65]
	v_lshlrev_b64 v[10:11], 13, v[10:11]
	v_lshl_add_u64 v[12:13], v[6:7], 0, v[10:11]
	v_add_u32_e32 v10, 32, v2
	v_ashrrev_i32_e32 v11, 31, v10
	v_lshlrev_b64 v[10:11], 13, v[10:11]
	v_lshl_add_u64 v[16:17], v[6:7], 0, v[10:11]
	v_add_u32_e32 v10, 40, v2
	v_ashrrev_i32_e32 v11, 31, v10
	v_ashrrev_i32_e32 v3, 31, v2
	v_lshlrev_b64 v[10:11], 13, v[10:11]
	v_lshlrev_b64 v[0:1], 13, v[2:3]
	v_add_u32_e32 v4, 8, v2
	v_add_u32_e32 v8, 16, v2
	v_lshl_add_u64 v[20:21], v[6:7], 0, v[10:11]
	v_add_u32_e32 v10, 48, v2
	v_add_u32_e32 v2, 56, v2
	v_ashrrev_i32_e32 v5, 31, v4
	v_ashrrev_i32_e32 v9, 31, v8
	v_ashrrev_i32_e32 v11, 31, v10
	v_ashrrev_i32_e32 v3, 31, v2
	v_lshlrev_b64 v[4:5], 13, v[4:5]
	v_lshlrev_b64 v[8:9], 13, v[8:9]
	v_lshlrev_b64 v[10:11], 13, v[10:11]
	v_lshlrev_b64 v[2:3], 13, v[2:3]
	v_lshl_add_u64 v[0:1], v[6:7], 0, v[0:1]
	v_lshl_add_u64 v[4:5], v[6:7], 0, v[4:5]
	v_lshl_add_u64 v[8:9], v[6:7], 0, v[8:9]
	v_lshl_add_u64 v[24:25], v[6:7], 0, v[10:11]
	v_lshl_add_u64 v[28:29], v[6:7], 0, v[2:3]
	s_mov_b64 s[86:87], 0
